# combination: K-fragment prefetch behind the per-step barrier + LDS-DMA block without s_nop fillers, on top of the tile-B max-tree reorder
# baseline (speedup 1.0000x reference)
; template <bool HAS_QK, bool HAS_PV> ...
;     ...
;     if (HAS_QK) {
;         const float c0 = beta - mrun;
; #pragma unroll
;         for (int r = 0; r < 16; ++r) { s0[r] = c0; s1[r] = c0; }
; #pragma unroll
;         for (int s4 = 0; s4 < 4; ++s4) {
;             const bf16x8 a0 = KFRAG(Kt, kb0, kb1, 0, 0, s4), a1 = KFRAG(Kt, kb0, kb1, 1, 0, s4);
;             s0 = __builtin_amdgcn_mfma_f32_32x32x16_bf16(a0, qf[s4], s0, 0, 0, 0);
;             s1 = __builtin_amdgcn_mfma_f32_32x32x16_bf16(a1, qf[s4], s1, 0, 0, 0);
;         }
.Lcreg_ok_a:
	s_andn2_b64 vcc, exec, s[4:5]
	v_mfma_f32_32x32x16_bf16 v[128:143], v[2:5], v[144:147], v[194:209]
	ds_read_b128 v[220:223], v248 offset:512
	v_mfma_f32_32x32x16_bf16 v[80:95], v[6:9], v[144:147], v[194:209]
	ds_read_b128 v[224:227], v248 offset:8704
	v_mfma_f32_32x32x16_bf16 v[128:143], v[10:13], v[148:151], v[128:143]
	ds_read_b128 v[228:231], v249 offset:512
	v_mfma_f32_32x32x16_bf16 v[80:95], v[182:185], v[148:151], v[80:95]
	ds_read_b128 v[232:235], v249 offset:8704
	s_waitcnt lgkmcnt(3)
	v_mfma_f32_32x32x16_bf16 v[128:143], v[220:223], v[152:155], v[128:143]
	s_waitcnt lgkmcnt(2)
	v_mfma_f32_32x32x16_bf16 v[80:95], v[224:227], v[152:155], v[80:95]
	s_waitcnt lgkmcnt(1)
	v_mfma_f32_32x32x16_bf16 v[128:143], v[228:231], v[156:159], v[128:143]
	s_waitcnt lgkmcnt(0)
	v_mfma_f32_32x32x16_bf16 v[80:95], v[232:235], v[156:159], v[80:95]
	s_cmp_ge_u32 s35, s17
	s_cbranch_scc1 .Ldiff_nodma
	s_and_b32 s4, s34, 0x10000
	s_add_i32 s4, s24, s4
	v_readlane_b32 s10, v247, 0
	v_readlane_b32 s11, v247, 1
	s_add_i32 s56, s29, 0x80
	s_lshl_b32 s56, s56, 10
	s_add_u32 s10, s10, s56
	s_addc_u32 s11, s11, 0
	s_mov_b32 m0, s4
	s_add_u32 s56, s10, s72
	s_addc_u32 s57, s11, s73
	global_load_lds_dwordx4 v250, s[56:57]
	s_add_i32 m0, s4, 0x2000
	ds_read_b128 v[220:223], v248 offset:32768
	global_load_lds_dwordx4 v251, s[56:57]
	s_add_i32 m0, s4, 0x4000
	s_add_u32 s56, s10, s74
	s_addc_u32 s57, s11, s75
	global_load_lds_dwordx4 v250, s[56:57]
	s_add_i32 m0, s4, 0x6000
	ds_read_b128 v[224:227], v249 offset:32768
	global_load_lds_dwordx4 v251, s[56:57]
	s_add_i32 m0, s4, 0x8000
	s_add_u32 s56, s10, s68
	s_addc_u32 s57, s11, s69
	global_load_lds_dwordx4 v250, s[56:57]
	s_add_i32 m0, s4, 0xa000
	ds_read_b128 v[228:231], v248 offset:33280
	global_load_lds_dwordx4 v251, s[56:57]
	s_add_i32 m0, s4, 0xc000
	s_add_u32 s56, s10, s96
	s_addc_u32 s57, s11, s97
	global_load_lds_dwordx4 v250, s[56:57]
	s_add_i32 m0, s4, 0xe000
	ds_read_b128 v[232:235], v249 offset:33280
	global_load_lds_dwordx4 v251, s[56:57]
	s_branch .Ldiff_dma_done
